# merged GEMM: two more gate quads carried between units in v248-v255 (VGPR allocation 248->256, still 2 waves/SIMD)
# speedup vs baseline: 1.0025x; 1.0025x over previous
;     __device__ __forceinline__ void operator()(acc_t& acc, const Unit& u, int wr, int wc, int fr, int fq) const {
;     ...
;             u32x4 ga[4][2], gb[4][2];
; #pragma unroll
;             for (int m = 0; m < 4; ++m)
; #pragma unroll
;                 for (int bj = 0; bj < 2; ++bj) { const size_t o = (size_t)(ai * HALF + m * 16) * D + HALF * bj; ga[m][bj] = *(const u32x4*)(Ga + o); if (br < 2) gb[m][bj] = *(const u32x4*)(Gb + o); }
.LBB0_653:
	s_and_b64 vcc, exec, s[64:65]
	s_cbranch_vccz .Lp3t_skipa
	v_add_co_u32_e32 v244, vcc, 0x58000, v200
	s_nop 1
	v_addc_co_u32_e32 v245, vcc, 0, v201, vcc
	global_load_dwordx4 v[248:251], v[244:245], off nt
.Lp3t_skipa:
	s_and_b64 vcc, exec, s[4:5]
	s_cbranch_vccnz .Lp3t_6
	v_add_co_u32_e32 v244, vcc, 0x58000, v198
	s_nop 1
	v_addc_co_u32_e32 v245, vcc, 0, v199, vcc
	global_load_dwordx4 v[134:137], v[244:245], off
.Lp3t_6:
	s_and_b64 vcc, exec, s[64:65]
	s_cbranch_vccz .Lp3t_skipb
	v_add_co_u32_e32 v244, vcc, 0x58000, v200
	s_nop 1
	v_addc_co_u32_e32 v245, vcc, 0, v201, vcc
	global_load_dwordx4 v[252:255], v[244:245], off offset:256 nt
.Lp3t_skipb:
	s_and_b64 vcc, exec, s[4:5]
	s_cbranch_vccnz .Lp3t_7
	v_add_co_u32_e32 v244, vcc, 0x58000, v198
	s_nop 1
	v_addc_co_u32_e32 v245, vcc, 0, v199, vcc
	global_load_dwordx4 v[130:133], v[244:245], off offset:256

; __device__ __forceinline__ float clampg(unsigned bits) { return __uint_as_float(bits > 0x0da24260u ? bits : 0x0da24260u); }
;     __device__ __forceinline__ void operator()(acc_t& acc, const Unit& u, int wr, int wc, int fr, int fq) const {
;     ...
;                     const u32x4 a = ga[m][bj]; float f[8] = {clampg(a.x << 16), clampg(a.x & 0xffff0000u), clampg(a.y << 16), clampg(a.y & 0xffff0000u), clampg(a.z << 16), clampg(a.z & 0xffff0000u), clampg(a.w << 16), clampg(a.w & 0xffff0000u)};
;                     if (br < 2) { const u32x4 b = gb[m][bj]; const float d[8] = {clampg(b.x << 16), clampg(b.x & 0xffff0000u), clampg(b.y << 16), clampg(b.y & 0xffff0000u), clampg(b.z << 16), clampg(b.z & 0xffff0000u), clampg(b.w << 16), clampg(b.w & 0xffff0000u)};
; #pragma unroll
;                         for (int e = 0; e < 8; ++e) f[e] *= __builtin_amdgcn_rcpf(d[e]); }
;                     f32x4 x0 = acc[ai][bj][m][0], x1 = acc[ai][bj][m][1];
;                     x0[0] *= f[0]; x0[1] *= f[1]; x0[2] *= f[2]; x0[3] *= f[3]; x1[0] *= f[4]; x1[1] *= f[5]; x1[2] *= f[6]; x1[3] *= f[7];
;                     if (br < 2) { acc[ai][bj][m][0] = x0; acc[ai][bj][m][1] = x1; }
.LBB0_711:
	s_waitcnt vmcnt(1)
	v_lshlrev_b32_e32 v138, 16, v248
	v_max_u32_e32 v142, 0xda24260, v138
	v_and_b32_e32 v138, 0xffff0000, v248
	v_max_u32_e32 v143, 0xda24260, v138
	v_lshlrev_b32_e32 v138, 16, v249
	v_max_u32_e32 v140, 0xda24260, v138
	v_and_b32_e32 v138, 0xffff0000, v249
	v_max_u32_e32 v141, 0xda24260, v138
	v_lshlrev_b32_e32 v138, 16, v250
	v_max_u32_e32 v144, 0xda24260, v138
	v_and_b32_e32 v138, 0xffff0000, v250
	v_max_u32_e32 v145, 0xda24260, v138
	v_lshlrev_b32_e32 v138, 16, v251
	v_and_b32_e32 v139, 0xffff0000, v251
	v_mov_b32_e32 v248, v134
	v_mov_b32_e32 v249, v135
	v_mov_b32_e32 v250, v136
	v_mov_b32_e32 v251, v137
	v_max_u32_e32 v138, 0xda24260, v138
	v_max_u32_e32 v139, 0xda24260, v139
	s_and_b64 vcc, exec, s[6:7]
	s_mov_b64 s[2:3], -1
	s_cbranch_vccnz .LBB0_713
	s_mov_b64 s[2:3], 0

; __device__ __forceinline__ float clampg(unsigned bits) { return __uint_as_float(bits > 0x0da24260u ? bits : 0x0da24260u); }
;     __device__ __forceinline__ void operator()(acc_t& acc, const Unit& u, int wr, int wc, int fr, int fq) const {
;     ...
;                     const u32x4 a = ga[m][bj]; float f[8] = {clampg(a.x << 16), clampg(a.x & 0xffff0000u), clampg(a.y << 16), clampg(a.y & 0xffff0000u), clampg(a.z << 16), clampg(a.z & 0xffff0000u), clampg(a.w << 16), clampg(a.w & 0xffff0000u)};
;                     if (br < 2) { const u32x4 b = gb[m][bj]; const float d[8] = {clampg(b.x << 16), clampg(b.x & 0xffff0000u), clampg(b.y << 16), clampg(b.y & 0xffff0000u), clampg(b.z << 16), clampg(b.z & 0xffff0000u), clampg(b.w << 16), clampg(b.w & 0xffff0000u)};
; #pragma unroll
;                         for (int e = 0; e < 8; ++e) f[e] *= __builtin_amdgcn_rcpf(d[e]); }
;                     f32x4 x0 = acc[ai][bj][m][0], x1 = acc[ai][bj][m][1];
;                     x0[0] *= f[0]; x0[1] *= f[1]; x0[2] *= f[2]; x0[3] *= f[3]; x1[0] *= f[4]; x1[1] *= f[5]; x1[2] *= f[6]; x1[3] *= f[7];
;                     if (br < 2) { acc[ai][bj][m][0] = x0; acc[ai][bj][m][1] = x1; }
.LBB0_718:
	s_waitcnt vmcnt(0)
	v_lshlrev_b32_e32 v134, 16, v252
	v_max_u32_e32 v138, 0xda24260, v134
	v_and_b32_e32 v134, 0xffff0000, v252
	v_max_u32_e32 v139, 0xda24260, v134
	v_lshlrev_b32_e32 v134, 16, v253
	v_max_u32_e32 v136, 0xda24260, v134
	v_and_b32_e32 v134, 0xffff0000, v253
	v_max_u32_e32 v137, 0xda24260, v134
	v_lshlrev_b32_e32 v134, 16, v254
	v_max_u32_e32 v140, 0xda24260, v134
	v_and_b32_e32 v134, 0xffff0000, v254
	v_max_u32_e32 v141, 0xda24260, v134
	v_lshlrev_b32_e32 v134, 16, v255
	v_and_b32_e32 v135, 0xffff0000, v255
	v_mov_b32_e32 v252, v130
	v_mov_b32_e32 v253, v131
	v_mov_b32_e32 v254, v132
	v_mov_b32_e32 v255, v133
	v_max_u32_e32 v134, 0xda24260, v134
	v_max_u32_e32 v135, 0xda24260, v135
	s_and_b64 vcc, exec, s[6:7]
	s_mov_b64 s[2:3], -1
	s_cbranch_vccnz .LBB0_720
	s_mov_b64 s[2:3], 0

; __global__ void __launch_bounds__(NTHREADS, 2) skel_fwd(Args args) {
	.amdhsa_kernel _Z8skel_fwd4Args
		.amdhsa_group_segment_fixed_size 0
		.amdhsa_private_segment_fixed_size 0
		.amdhsa_kernarg_size 432
		.amdhsa_user_sgpr_count 2
		.amdhsa_user_sgpr_dispatch_ptr 0
		.amdhsa_user_sgpr_queue_ptr 0
		.amdhsa_user_sgpr_kernarg_segment_ptr 1
		.amdhsa_user_sgpr_dispatch_id 0
		.amdhsa_user_sgpr_kernarg_preload_length 0
		.amdhsa_user_sgpr_kernarg_preload_offset 0
		.amdhsa_user_sgpr_private_segment_size 0
		.amdhsa_uses_dynamic_stack 0
		.amdhsa_enable_private_segment 0
		.amdhsa_system_sgpr_workgroup_id_x 1
		.amdhsa_system_sgpr_workgroup_id_y 0
		.amdhsa_system_sgpr_workgroup_id_z 0
		.amdhsa_system_sgpr_workgroup_info 0
		.amdhsa_system_vgpr_workitem_id 0
		.amdhsa_next_free_vgpr 256
		.amdhsa_next_free_sgpr 98
		.amdhsa_accum_offset 256
		.amdhsa_reserve_vcc 1
		.amdhsa_float_round_mode_32 0
		.amdhsa_float_round_mode_16_64 0
		.amdhsa_float_denorm_mode_32 3
		.amdhsa_float_denorm_mode_16_64 3
		.amdhsa_dx10_clamp 1
		.amdhsa_ieee_mode 1
		.amdhsa_fp16_overflow 0
		.amdhsa_tg_split 0
		.amdhsa_exception_fp_ieee_invalid_op 0
		.amdhsa_exception_fp_denorm_src 0
		.amdhsa_exception_fp_ieee_div_zero 0
		.amdhsa_exception_fp_ieee_overflow 0
		.amdhsa_exception_fp_ieee_underflow 0
		.amdhsa_exception_fp_ieee_inexact 0
		.amdhsa_exception_int_div_zero 0
	.end_amdhsa_kernel

; __global__ void __launch_bounds__(NTHREADS, 2) skel_fwd(Args args) {
amdhsa.kernels:
  - .agpr_count:     0
    .args:
      - .offset:         0
        .size:           176
        .value_kind:     by_value
      - .offset:         176
        .size:           4
        .value_kind:     hidden_block_count_x
      - .offset:         180
        .size:           4
        .value_kind:     hidden_block_count_y
      - .offset:         184
        .size:           4
        .value_kind:     hidden_block_count_z
      - .offset:         188
        .size:           2
        .value_kind:     hidden_group_size_x
      - .offset:         190
        .size:           2
        .value_kind:     hidden_group_size_y
      - .offset:         192
        .size:           2
        .value_kind:     hidden_group_size_z
      - .offset:         194
        .size:           2
        .value_kind:     hidden_remainder_x
      - .offset:         196
        .size:           2
        .value_kind:     hidden_remainder_y
      - .offset:         198
        .size:           2
        .value_kind:     hidden_remainder_z
      - .offset:         216
        .size:           8
        .value_kind:     hidden_global_offset_x
      - .offset:         224
        .size:           8
        .value_kind:     hidden_global_offset_y
      - .offset:         232
        .size:           8
        .value_kind:     hidden_global_offset_z
      - .offset:         240
        .size:           2
        .value_kind:     hidden_grid_dims
      - .offset:         296
        .size:           4
        .value_kind:     hidden_dynamic_lds_size
    .group_segment_fixed_size: 0
    .kernarg_segment_align: 8
    .kernarg_segment_size: 432
    .language:       OpenCL C
    .language_version:
      - 2
      - 0
    .max_flat_workgroup_size: 512
    .name:           _Z8skel_fwd4Args
    .private_segment_fixed_size: 0
    .sgpr_count:     104
    .sgpr_spill_count: 113
    .symbol:         _Z8skel_fwd4Args.kd
    .uniform_work_group_size: 1
    .uses_dynamic_stack: false
    .vgpr_count:     256
    .vgpr_spill_count: 0
    .wavefront_size: 64
